# chain wave: next step's 15 LDS operand reads issued speculatively in the shadow of the output tail (flag read first, counted lgkmcnt), on top of the deferred-publish version
# baseline (speedup 1.0000x reference)
; #define LAS __attribute__((address_space(3)))
; __device__ void phase_rwkv_dist(const Params& p, LAS unsigned char* lds, int wg, int nwg) {
;     ...
;             for (int ci = 0; ci < RC_NCHK; ++ci) {
;                 { unsigned sp = 0; while (!dead && lflag[ci % RD_NL] != (unsigned)(ci + 1)) { __builtin_amdgcn_s_sleep(1); if (++sp > RD_SPIN_MAX) { if (lane == 0) atomicAdd(ERR, 1u); dead = true; } } }
;                 asm volatile("" ::: "memory");
;                 LAS const unsigned char* sl = lds + (ci % RD_NL) * RC_SL;
;                 const bf16x8 at0 = *(LAS const bf16x8*)(sl + RC_AT + lane * 16), at1 = *(LAS const bf16x8*)(sl + RC_AT + 1024 + lane * 16);
;                 const bf16x8 rt0 = *(LAS const bf16x8*)(sl + RC_RT + lane * 16), rt1 = *(LAS const bf16x8*)(sl + RC_RT + 1024 + lane * 16);
;                 const bf16x8 mm0 = *(LAS const bf16x8*)(sl + RD_MM + lane * 32), mm1 = *(LAS const bf16x8*)(sl + RD_MM + lane * 32 + 16);
;                 const bf16x4 vt = *(LAS const bf16x4*)(sl + RC_VT + lane * 8);
;                 bf16x8 bk[4]; f32x4 gl[4];
; #pragma unroll
;                 for (int ct = 0; ct < 4; ++ct) { bk[ct] = *(LAS const bf16x8*)(sl + RD_BK + (ct * 64 + lane) * 16); gl[ct] = *(LAS const f32x4*)(sl + RC_GL + (16 * ct + 4 * q) * 4); }
;                 asm volatile("s_waitcnt lgkmcnt(0)" ::: "memory");
;                 lflag[12] = (unsigned)(ci + 1);
;                 const bf16x4 mak = __builtin_shufflevector(mm0, mm0, 0, 1, 2, 3), mrb = __builtin_shufflevector(mm0, mm0, 4, 5, 6, 7), mrk = __builtin_shufflevector(mm1, mm1, 0, 1, 2, 3), ti = __builtin_shufflevector(mm1, mm1, 4, 5, 6, 7);
;                 const bf16x8 sop0 = pk8(Sacc[0], Sacc[1]), sop1 = pk8(Sacc[2], Sacc[3]);
;                 f32x4 X = MFMA32(at0, sop0, zero4); X = MFMA32(at1, sop1, X); X = MFMA16(mak, vt, X);
;                 const f32x4 U = MFMA16(ti, pk4(X), zero4);
;                 const bf16x4 up = pk4(U);
;                 f32x4 Y = MFMA32(rt0, sop0, zero4); Y = MFMA32(rt1, sop1, Y); Y = MFMA16(mrb, up, Y); Y = MFMA16(mrk, vt, Y);
; #pragma unroll
;                 for (int ct = 0; ct < 4; ++ct) { const bf16x4 btc = __builtin_shufflevector(bk[ct], bk[ct], 0, 1, 2, 3), ktc = __builtin_shufflevector(bk[ct], bk[ct], 4, 5, 6, 7);
;                     Sacc[ct] = MFMA16(btc, up, Sacc[ct]); Sacc[ct] = MFMA16(ktc, vt, Sacc[ct]); Sacc[ct] = Sacc[ct] * gl[ct]; }
.LBB0_778:
	s_waitcnt lgkmcnt(0)
	s_mulk_i32 s16, 0x2b00
	s_add_i32 s2, s16, 0
	s_mul_hi_u32 s98, s7, 0xaaaaaaab
	s_lshr_b32 s98, s98, 3
	s_mul_i32 s98, s98, 12
	s_sub_i32 s98, s7, s98
	s_mul_i32 s99, s98, 0x2b00
	s_lshl_b32 s98, s98, 2
	s_add_i32 s98, s98, 0x27400
	v_add_u32_e32 v0, s2, v196
	v_add_u32_e32 v90, s2, v198
	v_add_u32_e32 v82, s2, v203
	v_add_u32_e32 v98, s2, v189
	ds_read_b128 v[104:107], v0
	ds_read_b128 v[108:111], v0 offset:1024
	ds_read_b128 v[112:115], v90 offset:8192
	ds_read_b64 v[102:103], v82 offset:10240
	ds_read_b128 v[120:123], v90 offset:8208
	ds_read_b128 v[116:119], v0 offset:2048
	ds_read_b128 v[128:131], v0 offset:3072
	ds_read_b128 v[132:135], v0 offset:4096
	ds_read_b128 v[136:139], v0 offset:5120
	ds_read_b128 v[140:143], v0 offset:6144
	ds_read_b128 v[144:147], v0 offset:7168
	ds_read_b128 v[124:127], v98 offset:10752
	ds_read_b128 v[160:163], v98 offset:10816
	ds_read_b128 v[168:171], v98 offset:10880
	ds_read_b128 v[176:179], v98 offset:10944
.Lch_body:
	v_cvt_pk_bf16_f32 v82, v56, v57
	v_cvt_pk_bf16_f32 v83, v58, v59
	v_cvt_pk_bf16_f32 v84, v64, v65
	v_cvt_pk_bf16_f32 v85, v66, v67
	v_cvt_pk_bf16_f32 v86, v60, v61
	v_cvt_pk_bf16_f32 v87, v62, v63
	v_cvt_pk_bf16_f32 v88, v52, v53
	v_cvt_pk_bf16_f32 v89, v54, v55
	s_lshl_b32 s72, s6, 4
	s_cmpk_eq_i32 s7, 0x200
	s_mov_b32 s6, s7
	s_waitcnt lgkmcnt(14)
	v_mfma_f32_16x16x32_bf16 v[70:73], v[104:107], v[82:85], 0
	s_waitcnt lgkmcnt(13)
	v_mfma_f32_16x16x32_bf16 v[70:73], v[108:111], v[86:89], v[70:73]
	s_waitcnt lgkmcnt(9)
	v_mfma_f32_16x16x32_bf16 v[180:183], v[116:119], v[82:85], 0
	s_waitcnt lgkmcnt(8)
	v_mfma_f32_16x16x32_bf16 v[180:183], v[128:131], v[86:89], v[180:183]
	s_nop 4
	v_mfma_f32_16x16x16_bf16 v[70:73], v[112:113], v[102:103], v[70:73]
	s_nop 7
	v_cvt_pk_bf16_f32 v70, v70, v71
	v_cvt_pk_bf16_f32 v71, v72, v73
	s_nop 1
	v_mfma_f32_16x16x16_bf16 v[70:73], v[122:123], v[70:71], 0
	s_nop 3
	v_mfma_f32_16x16x16_bf16 v[180:183], v[120:121], v[102:103], v[180:183]
	s_nop 2
	v_cvt_pk_bf16_f32 v88, v70, v71
	v_cvt_pk_bf16_f32 v89, v72, v73
	s_waitcnt lgkmcnt(4)
	s_nop 0
	v_mfma_f32_16x16x16_bf16 v[56:59], v[132:133], v[88:89], v[56:59]
	v_mfma_f32_16x16x16_bf16 v[64:67], v[136:137], v[88:89], v[64:67]
	v_mfma_f32_16x16x16_bf16 v[60:63], v[140:141], v[88:89], v[60:63]
	v_mfma_f32_16x16x16_bf16 v[52:55], v[144:145], v[88:89], v[52:55]
	v_mfma_f32_16x16x16_bf16 v[56:59], v[134:135], v[102:103], v[56:59]
	v_mfma_f32_16x16x16_bf16 v[64:67], v[138:139], v[102:103], v[64:67]
	v_mfma_f32_16x16x16_bf16 v[60:63], v[142:143], v[102:103], v[60:63]
	v_mfma_f32_16x16x16_bf16 v[52:55], v[146:147], v[102:103], v[52:55]
	v_mfma_f32_16x16x16_bf16 v[180:183], v[114:115], v[88:89], v[180:183]
	s_waitcnt lgkmcnt(0)
	v_mov_b32_e32 v0, s50
	v_mov_b32_e32 v184, s7
	ds_write_b32 v0, v184
	v_mov_b32_e32 v185, s98
	ds_read_b32 v185, v185
	v_add_u32_e32 v0, s99, v196
	v_add_u32_e32 v90, s99, v198
	v_add_u32_e32 v82, s99, v203
	v_add_u32_e32 v98, s99, v189
	ds_read_b128 v[104:107], v0
	ds_read_b128 v[108:111], v0 offset:1024
	ds_read_b128 v[112:115], v90 offset:8192
	ds_read_b64 v[102:103], v82 offset:10240
	ds_read_b128 v[120:123], v90 offset:8208
	ds_read_b128 v[116:119], v0 offset:2048
	ds_read_b128 v[128:131], v0 offset:3072
	ds_read_b128 v[132:135], v0 offset:4096
	ds_read_b128 v[136:139], v0 offset:5120
	ds_read_b128 v[140:143], v0 offset:6144
	ds_read_b128 v[144:147], v0 offset:7168
	v_pk_mul_f32 v[56:57], v[124:125], v[56:57]
	v_pk_mul_f32 v[58:59], v[126:127], v[58:59]
	v_pk_mul_f32 v[64:65], v[160:161], v[64:65]
	v_pk_mul_f32 v[66:67], v[162:163], v[66:67]
	v_pk_mul_f32 v[60:61], v[168:169], v[60:61]
	v_pk_mul_f32 v[62:63], v[170:171], v[62:63]
	v_pk_mul_f32 v[52:53], v[176:177], v[52:53]
	v_pk_mul_f32 v[54:55], v[178:179], v[54:55]
	s_waitcnt lgkmcnt(11)
	ds_read_b128 v[124:127], v98 offset:10752
	ds_read_b128 v[160:163], v98 offset:10816
	ds_read_b128 v[168:171], v98 offset:10880
	ds_read_b128 v[176:179], v98 offset:10944
	v_cvt_pk_bf16_f32 v70, v180, v181
	v_cvt_pk_bf16_f32 v71, v182, v183
	v_lshl_add_u64 v[166:167], v[2:3], 0, s[72:73]
	v_lshlrev_b64 v[166:167], 7, v[166:167]
	v_mfma_f32_16x16x16_bf16 v[70:73], v[70:71], v[150:151], 0
	v_lshl_add_u64 v[166:167], v[68:69], 0, v[166:167]
	s_nop 7
	v_cvt_pk_bf16_f32 v70, v70, v71
	v_cvt_pk_bf16_f32 v71, v72, v73
	global_store_dwordx2 v[166:167], v[70:71], off
	s_cbranch_scc1 .LBB0_789
.LBB0_779:
	s_mul_hi_u32 s2, s6, 0xaaaaaaab
	s_lshr_b32 s2, s2, 3
	s_mul_i32 s2, s2, 12
	s_sub_i32 s16, s6, s2
	s_add_i32 s7, s6, 1
	s_and_b64 vcc, exec, s[0:1]
	s_mov_b64 s[0:1], -1
	s_cbranch_vccnz .LBB0_778
	s_lshl_b32 s0, s16, 2
	s_add_i32 s17, s0, 0
	s_add_i32 s17, s17, 0x27400
	s_mov_b32 s18, 0
	s_waitcnt lgkmcnt(15)
	v_cmp_eq_u32_e32 vcc, s7, v185
	s_cbranch_vccnz .Lch_fast
	s_branch .LBB0_782
.Lch_fast:
	s_mov_b64 s[0:1], 0
	s_mul_hi_u32 s98, s7, 0xaaaaaaab
	s_lshr_b32 s98, s98, 3
	s_mul_i32 s98, s98, 12
	s_sub_i32 s98, s7, s98
	s_mul_i32 s99, s98, 0x2b00
	s_lshl_b32 s98, s98, 2
	s_add_i32 s98, s98, 0x27400
	s_branch .Lch_body

; __device__ void phase_rwkv_dist(const Params& p, LAS unsigned char* lds, int wg, int nwg) {
;     ...
;             }
;             __builtin_amdgcn_s_setprio(0);
.LBB0_789:
	s_waitcnt lgkmcnt(0)
	s_mov_b64 s[2:3], -1
